# prep item rounds interleaved (bandwidth-bound fp8 conversion mixed with latency-bound transposes); attention softmax max trees reduced to v_max3
# speedup vs baseline: 1.1439x; 1.0158x over previous
; DEV void attn_item(const Params& p, int item, char* smem) {
;     ...
;     const bf16_t* Kc = Ks + (kt & 1) * (32 * ASTR);
;     const bf16_t* Vc = Vs + (kt & 1) * (64 * VSTR);
;     f32x16 s[2];
; #pragma unroll
;     for (int jt = 0; jt < 2; jt++) {
; #pragma unroll
;       for (int r = 0; r < 16; r++) s[jt][r] = 0.f;
; #pragma unroll
;       for (int ks = 0; ks < 6; ks++) {
;         bf16x8 kf = *(const bf16x8*)(Kc + c31 * ASTR + ks * 16 + hf * 8);
;         s[jt] = mfma32(kf, qf[jt][ks], s[jt]);
;       }
;     }
; #pragma unroll
;     for (int jt = 0; jt < 2; jt++) {
;       float m0 = fmaxf(fmaxf(s[jt][0], s[jt][1]), fmaxf(s[jt][2], s[jt][3]));
;       float m1 = fmaxf(fmaxf(s[jt][4], s[jt][5]), fmaxf(s[jt][6], s[jt][7]));
;       float m2 = fmaxf(fmaxf(s[jt][8], s[jt][9]), fmaxf(s[jt][10], s[jt][11]));
;       float m3 = fmaxf(fmaxf(s[jt][12], s[jt][13]), fmaxf(s[jt][14], s[jt][15]));
;       const float mx = fmaxf(fmaxf(m0, m1), fmaxf(m2, m3));
;       if (__any(mx > mrun[jt])) {
;         const float mxa = fmaxf(mx, __shfl_xor(mx, 32));
;         const float mnew = fmaxf(mrun[jt], mxa);
;         const float alpha = __builtin_amdgcn_exp2f(mrun[jt] - mnew);
;         mrun[jt] = mnew;
;         lrun[jt] *= alpha;
; #pragma unroll
;         for (int dt = 0; dt < 2; dt++)
; #pragma unroll
;           for (int r = 0; r < 16; r++) o[dt][jt][r] *= alpha;
;       }
;       const float mcur = mrun[jt];
;       float pv[16];
; #pragma unroll
;       for (int r = 0; r < 16; r++) pv[r] = __builtin_amdgcn_exp2f(s[jt][r] - mcur);
;       lrun[jt] += (((pv[0] + pv[1]) + (pv[2] + pv[3])) + ((pv[4] + pv[5]) + (pv[6] + pv[7]))) +
;                   (((pv[8] + pv[9]) + (pv[10] + pv[11])) + ((pv[12] + pv[13]) + (pv[14] + pv[15])));
;       bf16x8 pf[2];
; #pragma unroll
;       for (int ss = 0; ss < 2; ss++) {
;         uint4 u; u.x = pack2(pv[8 * ss + 0], pv[8 * ss + 1]); u.y = pack2(pv[8 * ss + 2], pv[8 * ss + 3]);
;         u.z = pack2(pv[8 * ss + 4], pv[8 * ss + 5]); u.w = pack2(pv[8 * ss + 6], pv[8 * ss + 7]);
;         pf[ss] = __builtin_bit_cast(bf16x8, u);
;       }
; #pragma unroll
;       for (int dt = 0; dt < 2; dt++)
; #pragma unroll
;         for (int ss = 0; ss < 2; ss++) {
;           uint2 lo = *(const uint2*)(Vc + (dt * 32 + c31) * VSTR + 16 * ss + 4 * hf);
;           uint2 hi = *(const uint2*)(Vc + (dt * 32 + c31) * VSTR + 16 * ss + 8 + 4 * hf);
.LBB0_753:
	s_and_b32 s11, s12, 1
	s_mul_i32 s10, s11, 0x1a00
	v_add_u32_e32 v0, s10, v187
	ds_read_b128 v[2:5], v0
	ds_read_b128 v[6:9], v0 offset:32
	ds_read_b128 v[10:13], v0 offset:64
	ds_read_b128 v[240:243], v0 offset:96
	ds_read_b128 v[244:247], v0 offset:128
	ds_read_b128 v[236:239], v0 offset:160
	s_waitcnt lgkmcnt(5)
	v_mfma_f32_32x32x16_bf16 v[96:111], v[2:5], v[156:159], 0
	s_waitcnt lgkmcnt(4)
	v_mfma_f32_32x32x16_bf16 v[96:111], v[6:9], v[152:155], v[96:111]
	v_mfma_f32_32x32x16_bf16 v[80:95], v[2:5], v[132:135], 0
	s_waitcnt lgkmcnt(3)
	v_mfma_f32_32x32x16_bf16 v[96:111], v[10:13], v[148:151], v[96:111]
	v_mfma_f32_32x32x16_bf16 v[80:95], v[6:9], v[128:131], v[80:95]
	s_waitcnt lgkmcnt(2)
	v_mfma_f32_32x32x16_bf16 v[96:111], v[240:243], v[144:147], v[96:111]
	v_mfma_f32_32x32x16_bf16 v[80:95], v[10:13], v[112:115], v[80:95]
	s_waitcnt lgkmcnt(1)
	v_mfma_f32_32x32x16_bf16 v[96:111], v[244:247], v[140:143], v[96:111]
	v_mfma_f32_32x32x16_bf16 v[80:95], v[240:243], v[116:119], v[80:95]
	s_waitcnt lgkmcnt(0)
	v_mfma_f32_32x32x16_bf16 v[96:111], v[236:239], v[136:139], v[96:111]
	v_mfma_f32_32x32x16_bf16 v[80:95], v[244:247], v[120:123], v[80:95]
	s_nop 10
	v_max3_f32 v0, v96, v97, v98
	v_max3_f32 v2, v99, v100, v101
	v_max3_f32 v3, v102, v103, v104
	v_max3_f32 v4, v105, v106, v107
	v_mfma_f32_32x32x16_bf16 v[80:95], v[236:239], v[124:127], v[80:95]
	v_max3_f32 v5, v108, v109, v110
	v_max3_f32 v0, v0, v2, v111
	v_max3_f32 v3, v3, v4, v5
	v_max_f32_e32 v0, v0, v3
	v_cmp_gt_f32_e32 vcc, v0, v185
	s_cbranch_vccz .LBB0_755
	v_mbcnt_hi_u32_b32 v2, -1, v215
	v_and_b32_e32 v4, 64, v2
	v_xor_b32_e32 v3, 32, v2
	v_add_u32_e32 v4, 64, v4
	v_cmp_lt_i32_e32 vcc, v3, v4
	s_nop 1
	v_cndmask_b32_e32 v2, v2, v3, vcc
	v_lshlrev_b32_e32 v2, 2, v2
	ds_bpermute_b32 v2, v2, v0
	s_waitcnt lgkmcnt(0)
	v_max3_f32 v2, v185, v0, v2
	v_sub_f32_e32 v0, v185, v2
	v_exp_f32_e32 v0, v0
	v_mov_b32_e32 v185, v2
	v_mul_f32_e32 v14, v14, v0
	v_pk_mul_f32 v[46:47], v[46:47], v[0:1] op_sel_hi:[1,0]
	v_pk_mul_f32 v[44:45], v[44:45], v[0:1] op_sel_hi:[1,0]
	v_pk_mul_f32 v[42:43], v[42:43], v[0:1] op_sel_hi:[1,0]
	v_pk_mul_f32 v[40:41], v[40:41], v[0:1] op_sel_hi:[1,0]
	v_pk_mul_f32 v[38:39], v[38:39], v[0:1] op_sel_hi:[1,0]
	v_pk_mul_f32 v[36:37], v[36:37], v[0:1] op_sel_hi:[1,0]
	v_pk_mul_f32 v[34:35], v[34:35], v[0:1] op_sel_hi:[1,0]
	v_pk_mul_f32 v[32:33], v[32:33], v[0:1] op_sel_hi:[1,0]
	v_pk_mul_f32 v[30:31], v[30:31], v[0:1] op_sel_hi:[1,0]
	v_pk_mul_f32 v[28:29], v[28:29], v[0:1] op_sel_hi:[1,0]
	v_pk_mul_f32 v[26:27], v[26:27], v[0:1] op_sel_hi:[1,0]
	v_pk_mul_f32 v[24:25], v[24:25], v[0:1] op_sel_hi:[1,0]
	v_pk_mul_f32 v[22:23], v[22:23], v[0:1] op_sel_hi:[1,0]
	v_pk_mul_f32 v[20:21], v[20:21], v[0:1] op_sel_hi:[1,0]
	v_pk_mul_f32 v[18:19], v[18:19], v[0:1] op_sel_hi:[1,0]
	v_pk_mul_f32 v[16:17], v[16:17], v[0:1] op_sel_hi:[1,0]
.LBB0_755:
	v_sub_f32_e32 v2, v97, v185
	v_exp_f32_e32 v193, v2
	v_sub_f32_e32 v2, v98, v185
	v_exp_f32_e32 v194, v2
	v_sub_f32_e32 v2, v99, v185
	v_exp_f32_e32 v239, v2
	v_sub_f32_e32 v2, v100, v185
	v_exp_f32_e32 v100, v2
	v_sub_f32_e32 v2, v101, v185
	v_exp_f32_e32 v101, v2
	v_sub_f32_e32 v2, v102, v185
	v_exp_f32_e32 v102, v2
	v_sub_f32_e32 v2, v103, v185
	v_exp_f32_e32 v240, v2
	v_sub_f32_e32 v2, v104, v185
	v_exp_f32_e32 v103, v2
	v_sub_f32_e32 v2, v105, v185
	v_exp_f32_e32 v104, v2
	v_sub_f32_e32 v2, v106, v185
	v_exp_f32_e32 v105, v2
	v_sub_f32_e32 v2, v107, v185
	v_exp_f32_e32 v106, v2
	v_sub_f32_e32 v2, v108, v185
	s_mulk_i32 s11, 0x1600
	v_exp_f32_e32 v107, v2
	v_sub_f32_e32 v2, v109, v185
	v_exp_f32_e32 v108, v2
	v_sub_f32_e32 v2, v110, v185
	v_add_u32_e32 v10, s11, v177
	v_exp_f32_e32 v109, v2
	v_sub_f32_e32 v2, v111, v185
	v_add_u32_e32 v6, 0x3000, v10
	v_add_u32_e32 v15, 0x3800, v10
	v_exp_f32_e32 v110, v2
	ds_read2_b64 v[2:5], v6 offset0:128 offset1:130
	ds_read2_b64 v[6:9], v6 offset0:132 offset1:134
	ds_read2_b64 v[10:13], v15 offset0:224 offset1:226
	v_sub_f32_e32 v0, v96, v185
	v_exp_f32_e32 v0, v0
	v_cvt_pk_bf16_f32 v97, v194, v239
	v_cvt_pk_bf16_f32 v98, v100, v101
	v_cvt_pk_bf16_f32 v99, v102, v240
	v_cvt_pk_bf16_f32 v96, v0, v193
	v_max3_f32 v111, v80, v81, v82
	v_cvt_pk_bf16_f32 v242, v103, v104
	s_waitcnt lgkmcnt(2)
	v_mfma_f32_32x32x16_bf16 v[32:47], v[2:5], v[96:99], v[32:47]
	v_cvt_pk_bf16_f32 v243, v105, v106
	v_cvt_pk_bf16_f32 v244, v107, v108
	v_cvt_pk_bf16_f32 v245, v109, v110
	v_max3_f32 v192, v83, v84, v85
	v_max3_f32 v236, v86, v87, v88
	v_max3_f32 v237, v89, v90, v91
	v_max3_f32 v238, v92, v93, v94
	s_waitcnt lgkmcnt(0)
	v_mfma_f32_32x32x16_bf16 v[16:31], v[10:13], v[96:99], v[16:31]
	ds_read2_b64 v[96:99], v15 offset0:228 offset1:230
	v_max3_f32 v15, v111, v192, v95
	v_max3_f32 v236, v236, v237, v238
	v_mfma_f32_32x32x16_bf16 v[32:47], v[6:9], v[242:245], v[32:47]
	s_nop 1
	v_max_f32_e32 v15, v15, v236
	s_waitcnt lgkmcnt(0)
	v_mfma_f32_32x32x16_bf16 v[16:31], v[96:99], v[242:245], v[16:31]
	v_cmp_gt_f32_e32 vcc, v15, v175
	s_cbranch_vccz .LBB0_757
	v_mbcnt_hi_u32_b32 v111, -1, v215
	v_and_b32_e32 v236, 64, v111
	v_xor_b32_e32 v192, 32, v111
	v_add_u32_e32 v236, 64, v236
	v_cmp_lt_i32_e32 vcc, v192, v236
	s_nop 1
	v_cndmask_b32_e32 v111, v111, v192, vcc
	v_lshlrev_b32_e32 v111, 2, v111
	ds_bpermute_b32 v111, v111, v15
	s_waitcnt lgkmcnt(0)
	v_max3_f32 v15, v175, v15, v111
	v_sub_f32_e32 v111, v175, v15
	v_exp_f32_e32 v192, v111
	v_mov_b32_e32 v175, v15
	v_mul_f32_e32 v184, v184, v192
	v_pk_mul_f32 v[78:79], v[78:79], v[192:193] op_sel_hi:[1,0]
	v_pk_mul_f32 v[76:77], v[76:77], v[192:193] op_sel_hi:[1,0]
	v_pk_mul_f32 v[74:75], v[74:75], v[192:193] op_sel_hi:[1,0]
	v_pk_mul_f32 v[72:73], v[72:73], v[192:193] op_sel_hi:[1,0]
	v_pk_mul_f32 v[70:71], v[70:71], v[192:193] op_sel_hi:[1,0]
	v_pk_mul_f32 v[68:69], v[68:69], v[192:193] op_sel_hi:[1,0]
	v_pk_mul_f32 v[66:67], v[66:67], v[192:193] op_sel_hi:[1,0]
	v_pk_mul_f32 v[64:65], v[64:65], v[192:193] op_sel_hi:[1,0]
	v_pk_mul_f32 v[62:63], v[62:63], v[192:193] op_sel_hi:[1,0]
	v_pk_mul_f32 v[60:61], v[60:61], v[192:193] op_sel_hi:[1,0]
	v_pk_mul_f32 v[58:59], v[58:59], v[192:193] op_sel_hi:[1,0]
	v_pk_mul_f32 v[56:57], v[56:57], v[192:193] op_sel_hi:[1,0]
	v_pk_mul_f32 v[54:55], v[54:55], v[192:193] op_sel_hi:[1,0]
	v_pk_mul_f32 v[52:53], v[52:53], v[192:193] op_sel_hi:[1,0]
	v_pk_mul_f32 v[50:51], v[50:51], v[192:193] op_sel_hi:[1,0]
	v_pk_mul_f32 v[48:49], v[48:49], v[192:193] op_sel_hi:[1,0]

; DEV void phase_prep(const Params& p, char* smem) {
;   for (int item = blockIdx.x; item < P0_ITEMS; item += gridDim.x) {
;     int it = item;
;     if (it < P0_TR) {
;       if (it < NT_WIN) { transpose_tile(p.in[I_WIN], 1024, 1440, WSP(bf16_t, S_WIN0), LDH, it, smem); continue; }
;       it -= NT_WIN;
;       if (it < NT_WUQ) { transpose_tile(p.in[I_WUQ], 256, 768, WSP(bf16_t, S_WUQ), 256, it, smem); continue; }
;       it -= NT_WUQ;
;       if (it < NT_WUKV) { transpose_tile(p.in[I_WUKV], 128, 1024, WSP(bf16_t, S_WUKV), 128, it, smem); continue; }
;       it -= NT_WUKV;
;       if (it < NT_WOUT) { transpose_tile(p.in[I_WOUT], 1024, 1024, WSP(bf16_t, S_WOUT0), LDH, it, smem); continue; }
;       it -= NT_WOUT;
;       if (it < NT_HGIN) { transpose_tile(p.in[I_HGWIN], 1024, 5120, WSP(bf16_t, S_WHGIN), LDH, it, smem); continue; }
;       it -= NT_HGIN;
;       if (it < NT_HGOUT) { transpose_tile(p.in[I_HGWOUT], 1024, 1024, WSP(bf16_t, S_WHGOUT), LDH, it, smem); continue; }
;       it -= NT_HGOUT;
;       int l = it >> 11; it &= 2047;
;       transpose_tile(p.in[I_PWQ] + (size_t)l * 1024 * 2048, 1024, 2048, WSP(bf16_t, S_WPQ) + (size_t)l * 2048 * LDH, LDH, it, smem);
;       continue;
;     }
;     it -= P0_TR;
;     if (it < P0_CV_SUBK) { convert_chunk(p.in[I_PSK], WSP(bf16_t, S_SUBK), it); continue; }
;     it -= P0_CV_SUBK;
;     if (it < P0_CV_U + P0_CV_V) {
;       const int isv = it >= P0_CV_U; const int r16 = isv ? it - P0_CV_U : it;
.LBB0_1062:
	s_andn2_b64 vcc, exec, s[0:1]
	s_cbranch_vccnz .LBB0_1137
	v_readlane_b32 s0, v252, 60
	v_readlane_b32 s1, v252, 61
	s_andn2_b64 vcc, exec, s[0:1]
	s_cbranch_vccnz .LBB0_1137
	s_add_u32 s0, s28, 0xbf80000
	s_addc_u32 s1, s29, 0
	s_add_u32 s2, s28, 0xc000000
	s_addc_u32 s3, s29, 0
	s_add_u32 s6, s28, 0xbf40000
	s_addc_u32 s7, s29, 0
	s_add_u32 s18, s28, 0xa5fd000
	s_addc_u32 s19, s29, 0
	s_add_u32 s8, s28, 0xc2a0000
	s_addc_u32 s9, s29, 0
	s_add_u32 s10, s28, 0xbe40000
	s_addc_u32 s11, s29, 0
	s_add_u32 s44, s28, 0xb5c0000
	s_addc_u32 s45, s29, 0
	s_add_u32 s22, s28, 0xb3a0000
	s_addc_u32 s23, s29, 0
	s_mov_b64 s[12:13], s[28:29]
	s_add_u32 s28, s12, 0xa900000
	s_addc_u32 s29, s13, 0
	s_add_u32 s30, s12, 0xa6e0000
	s_addc_u32 s31, s13, 0
	s_add_u32 s34, s12, 0xa6a0000
	s_addc_u32 s35, s13, 0
	s_add_u32 s36, s12, 0xa640000
	s_addc_u32 s37, s13, 0
	s_add_u32 s46, s12, 0xa300000
	s_addc_u32 s47, s13, 0
	v_readlane_b32 s12, v253, 19
	s_add_u32 s14, s12, 0xba000
	v_readlane_b32 s12, v253, 20
	s_movk_i32 s57, 0x2000
	s_mov_b64 s[20:21], 0x3000
	s_addc_u32 s15, s12, 0
	v_readlane_b32 s48, v253, 10
	s_mov_b32 s49, s51
	s_mov_b32 m0, s51
	s_branch .LBB0_1066
.LBB0_1065:
	s_add_i32 m0, m0, s86
	s_cmp_gt_i32 m0, 0x4792
	s_cbranch_scc1 .Lp0_exit
	s_lshr_b32 s12, m0, 9
	s_and_b32 s13, m0, 0x1ff
	s_cmp_lt_u32 s12, 32
	s_cbranch_scc1 .Lp0_low
	s_cmp_lt_u32 s12, 34
	s_cbranch_scc0 .Lp0_set
	s_sub_u32 s12, s12, 8
	s_branch .Lp0_set
.Lp0_low:
	s_and_b32 vcc_lo, s12, 3
	s_lshr_b32 s12, s12, 2
	s_cmp_eq_u32 vcc_lo, 3
	s_cbranch_scc1 .Lp0_cv
	s_mul_i32 s12, s12, 3
	s_add_u32 s12, s12, vcc_lo
	s_branch .Lp0_set
.Lp0_cv:
	s_add_u32 s12, s12, 26
.Lp0_set:
	s_lshl_b32 s12, s12, 9
	s_or_b32 s49, s12, s13
	s_add_i32 s48, s49, 0xffffbbed

; DEV void phase_prep(const Params& p, char* smem) {
;   for (int item = blockIdx.x; item < P0_ITEMS; item += gridDim.x) {
;     int it = item;
.LBB0_1135:
	s_cbranch_execz .LBB0_1094
	s_branch .LBB0_1095
.Lp0_exit:
	s_mov_b32 m0, 0
.LBB0_1136:
	v_readlane_b32 s30, v253, 11
	v_readlane_b32 s31, v253, 12
	s_movk_i32 s19, 0x880
	s_movk_i32 s23, 0x3fff
	s_movk_i32 s36, 0xa0
	s_mov_b64 s[34:35], 0x100
	s_mov_b64 s[46:47], 0x3000
	s_mov_b64 s[48:49], 0x4000
	s_movk_i32 s21, 0x2000
	v_readlane_b32 s57, v253, 63
